# MX: LDS image row pitch 528->544 B (conflict-free ds_read_b128 fragment reads under the 16-lane groups)
# speedup vs baseline: 1.0288x; 1.0089x over previous
; #define LAS __attribute__((address_space(3)))
; DI void phase_mixer(const Params& p, int seg, LAS unsigned char* lds, int G, int bid) {
;     int tid = threadIdx.x; asm volatile("" : "+v"(tid));
;     const int lane = tid & 63, wave = __builtin_amdgcn_readfirstlane(tid >> 6);
;     const int li = wave & 3, ks = wave >> 2;
;     bf16_t* P = (bf16_t*)(p.ws + WS_P);
;     const bf16_t* QK = (const bf16_t*)(p.ws + WS_QK);
;     const f32x4* t1 = (const f32x4*)(p.ws + WS_GTAB);
;     const f32x4* t2 = (const f32x4*)(p.ws + WS_T2);
;     float* dnb = (float*)(p.ws + WS_DN);
;     const float* dn2 = (const float*)(p.ws + WS_DN2);
;     float* csave = (float*)(p.ws + WS_CSAVE);
;     const unsigned ldsb = (unsigned)(size_t)lds;
;     for (int item = bid; item < 256; item += G) {
;         const int stream = (item >> 5) * 4 + (item & 3), vs = (item & 31) >> 2;
;         const int grp = stream >> 4, b = (stream >> 2) & 3, hh = stream & 3;
;         const bool stab = (grp == 0);
;         constexpr int nvt = 3;
;         const bf16_t *qb, *kb, *vb; int qpitch;
;         if (grp == 0) { qb = QK + hh * 256; kb = QK + 1024 + hh * 256; qpitch = 2048; vb = P + 2048 + hh * 256 + vs * 32; }
;         else { qb = P + 5120 + hh * 256; kb = P + 6144 + hh * 256; qpitch = NPC; vb = P + 7168 + hh * 256 + vs * 32; }
;         bf16_t* cellb = P + grp * 1024 + hh * 256 + vs * 32;
;         const int lrowb = b * SEG;
;         const float gdec = exp2f(64.0f * log2f(1.0f - exp2f(-5.0f - (float)hh)));
;     ...
;         f32x4 C[2][3];
;         if (seg == 0) {
; #pragma unroll
;             for (int a = 0; a < 2; ++a)
; #pragma unroll
;                 for (int v = 0; v < 3; ++v) C[a][v] = (f32x4){0.f, 0.f, 0.f, 0.f};
;         } else {
; #pragma unroll
;             for (int a = 0; a < 2; ++a)
; #pragma unroll
;                 for (int v = 0; v < 3; ++v) C[a][v] = *(const f32x4*)(csave + ((size_t)item * 6 + a * 3 + v) * 2048 + tid * 4);
;         }
;         for (int i = tid; i < 64 * 8; i += NT) { const int r = i >> 3, c2 = i & 7; *(LAS unsigned*)(lds + L_VI + r * VP2 + 64 + c2 * 4) = (c2 == 0) ? 0x00003F80u : 0u; }
;     ...
;         float g_c = MX_G(0);
;         MX_WRITE_CIMG(1.0f);
;         u32x4 pq[4], pk[4], pv; u32x2 pin[2]; float pden = 0.f, pcm = 0.f, pbc = 0.f, pmch = 0.f;
;         const unsigned voq = (unsigned)(((tid >> 5) * qpitch + (tid & 31) * 8) * 2);
.LBB0_569:
.LBB0_570:
	v_readlane_b32 s0, v252, 4
	v_readlane_b32 s1, v252, 5
	s_cmp_ge_i32 s70, s0
	s_cselect_b64 s[0:1], -1, 0
	s_cmp_lt_i32 s70, s33
	s_cselect_b64 s[8:9], -1, 0
	s_and_b64 s[0:1], s[0:1], s[8:9]
	s_andn2_b64 vcc, exec, s[0:1]
	v_readlane_b32 s0, v250, 58
	s_add_i32 s88, s0, 5
	s_cbranch_vccnz .LBB0_692
	v_mov_b32_e32 v136, v202
	v_readlane_b32 s0, v251, 40
	v_readlane_b32 s1, v251, 41
	v_ashrrev_i32_e32 v0, 6, v136
	s_andn2_b64 vcc, exec, s[0:1]
	v_readfirstlane_b32 s11, v0
	s_cbranch_vccnz .LBB0_624
	s_waitcnt vmcnt(0)
	v_lshlrev_b32_e32 v2, 2, v136
	v_readlane_b32 s0, v251, 42
	v_ashrrev_i32_e32 v3, 31, v2
	v_readlane_b32 s1, v251, 43
	s_lshl_b32 s6, s11, 6
	s_add_i32 s8, 0, 0x11000
	v_lshl_add_u64 v[138:139], v[2:3], 2, s[0:1]
	s_movk_i32 s0, 0x200
	v_and_b32_e32 v2, 15, v136
	v_bfe_u32 v3, v136, 4, 2
	v_ashrrev_i32_e32 v8, 2, v136
	v_lshlrev_b32_e32 v9, 4, v136
	v_lshlrev_b32_e32 v0, 4, v0
	s_and_b32 s9, s11, 3
	v_cmp_gt_i32_e64 s[40:41], s0, v136
	v_lshlrev_b32_e32 v5, 3, v3
	s_add_i32 s0, s8, s6
	v_and_b32_e32 v10, 48, v9
	v_mul_lo_u32 v11, v8, s96
	v_and_or_b32 v159, v0, 48, v2
	s_and_b32 s17, s11, -4
	v_and_b32_e32 v4, 63, v136
	v_add_u32_e32 v6, s0, v5
	v_or_b32_e32 v140, v10, v11
	v_mul_u32_u24_e32 v11, 0x2400, v159
	v_lshlrev_b32_e32 v0, 2, v3
	s_movk_i32 s0, 0x100
	s_cmp_lt_u32 s11, 4
	s_mov_b32 s18, 0x19200
	v_max_i32_e32 v13, 0, v136
	v_or_b32_e32 v3, v11, v0
	v_cmp_gt_i32_e64 s[42:43], s0, v136
	v_cmp_gt_u32_e64 s[44:45], 16, v4
	v_lshl_or_b32 v161, s9, 4, v2
	s_cselect_b64 s[0:1], -1, 0
	s_cmp_eq_u32 s17, 4
	v_lshl_add_u32 v219, v4, 2, s18
	v_bfe_u32 v4, v136, 2, 2
	v_sub_u32_e32 v13, v13, v136
	v_lshlrev_b32_e32 v7, 3, v136
	v_lshlrev_b32_e32 v142, 1, v3
	v_and_b32_e32 v3, 0x1f0, v9
	v_mul_u32_u24_e32 v9, 0x220, v161
	v_and_b32_e32 v12, 48, v136
	s_cselect_b64 s[70:71], -1, 0
	s_mov_b32 s22, 0x17600
	v_or_b32_e32 v4, v5, v4
	s_add_i32 s18, s6, 0
	v_add_u32_e32 v13, 0x1ff, v13
	v_and_b32_e32 v147, 0xf8, v7
	v_add3_u32 v163, 0, v9, v12
	v_add_u32_e32 v218, s22, v10
	v_mul_lo_u32 v220, v8, s37
	v_mul_u32_u24_e32 v8, 0x220, v4
	v_and_b32_e32 v7, 24, v7
	s_add_i32 s19, s18, 0x8800
	v_mul_u32_u24_e32 v4, 0x70, v4
	v_add_u32_e32 v137, 0x200, v136
	v_add_u32_e32 v9, 0x400, v136
	v_add_u32_e32 v10, 0x600, v136
	v_lshrrev_b32_e32 v14, 9, v13
	v_ashrrev_i32_e32 v145, 5, v136
	v_add3_u32 v221, s19, v7, v8
	v_add3_u32 v222, v7, s22, v4
	v_and_b32_e32 v4, 7, v136
	v_mul_u32_u24_e32 v2, 0x220, v2
	v_ashrrev_i32_e32 v8, 5, v137
	v_ashrrev_i32_e32 v9, 5, v9
	v_ashrrev_i32_e32 v10, 5, v10
	s_add_i32 s18, s18, 0x11020
	v_add_u32_e32 v14, 1, v14
	v_mov_b32_e32 v141, v1
	v_add_u32_e32 v3, 0, v3
	v_cmp_eq_u32_e32 vcc, 0, v4
	v_mul_u32_u24_e32 v7, 0x220, v145
	v_mul_u32_u24_e32 v8, 0x220, v8
	v_mul_u32_u24_e32 v9, 0x220, v9
	v_mul_u32_u24_e32 v10, 0x220, v10
	s_or_b32 s97, s6, 0xc0
	v_add3_u32 v224, s8, v12, v2
	v_add_u32_e32 v12, s18, v5
	s_movk_i32 s6, 0x1ff
	v_and_b32_e32 v225, 0xfffffe, v14
	v_lshl_add_u32 v144, v4, 2, s22
	v_lshrrev_b32_e32 v4, 1, v136
	v_readlane_b32 s8, v250, 7
	v_mov_b32_e32 v143, v1
	v_cndmask_b32_e32 v223, 0, v214, vcc
	s_lshl_b32 s89, s17, 6
	s_mulk_i32 s9, 0xc00
	s_mulk_i32 s11, 0xc00
	v_cmp_lt_u32_e64 s[46:47], s6, v13
	v_lshl_add_u32 v226, v225, 9, v136
	v_cmp_ne_u32_e64 s[48:49], v14, v225
	v_and_b32_e32 v146, 24, v4
	v_or_b32_e32 v227, 64, v159
	v_lshl_add_u64 v[148:149], v[140:141], 0, s[56:57]
	v_lshl_or_b32 v150, v11, 1, v5
	v_mov_b32_e32 v151, v1
	v_lshlrev_b32_e32 v152, 1, v0
	v_add_u32_e32 v228, v6, v2
	v_add_u32_e32 v229, v3, v7
	v_add_u32_e32 v230, v3, v8
	v_add_u32_e32 v231, v3, v9
	v_add_u32_e32 v232, v3, v10
	v_add_u32_e32 v233, v12, v2
	v_readlane_b32 s38, v250, 8
	s_mov_b32 s39, s8
	s_branch .LBB0_574

; #define LAS __attribute__((address_space(3)))
; #define MX_LOADK(ch) do { const int r0_ = lrowb + (ch) * 64; const char* kr_ = (const char*)(kb + (size_t)r0_ * qpitch); \
;             _Pragma("unroll") for (int i = 0; i < 4; ++i) pk[i] = *(const u32x4*)(kr_ + i * qstep16 + voq); \
;             if (tid < 256) pv = *(const u32x4*)((const char*)(vb + (size_t)r0_ * NPC) + vov); } while (0)
; #define MX_STAGEQ() do { int ts_ = tid; \
;             _Pragma("unroll") for (int i = 0; i < 4; ++i) { const int idx = ts_ + 512 * i, row = idx >> 5, c16 = idx & 31; \
;                 *(LAS u32x4*)(lds + L_QI + row * QP + c16 * 16) = pq[i]; } } while (0)
; DI void phase_mixer(const Params& p, int seg, LAS unsigned char* lds, int G, int bid) {
;     ...
;         for (int i = tid; i < 64 * 8; i += NT) { const int r = i >> 3, c2 = i & 7; *(LAS unsigned*)(lds + L_VI + r * VP2 + 64 + c2 * 4) = (c2 == 0) ? 0x00003F80u : 0u; }
;     ...
;         float g_c = MX_G(0);
;         MX_WRITE_CIMG(1.0f);
;         u32x4 pq[4], pk[4], pv; u32x2 pin[2]; float pden = 0.f, pcm = 0.f, pbc = 0.f, pmch = 0.f;
;         const unsigned voq = (unsigned)(((tid >> 5) * qpitch + (tid & 31) * 8) * 2);
;         const unsigned vov = (unsigned)(((tid >> 2) * NPC + (tid & 3) * 8) * 2);
;         const unsigned vop = (unsigned)(((16 * ((tid >> 6) & 3) + (tid & 15)) * NPC + 4 * ((tid & 63) >> 4)) * 2);
;         const size_t qstep16 = (size_t)16 * qpitch * 2;
;     ...
;         u32x2 cin[2]; float cden = 0.f, cemr = 1.f;
;         MX_LOADQ(0);
;         MX_LOADK(0);
;         MX_STAGEQ();
;         cin[0] = pin[0]; cin[1] = pin[1]; cden = pden; cemr = __expf(-(pbc + fmaxf(pmch, pcm)));
.LBB0_586:
	s_bfe_u32 vcc_hi, s8, 0x30002
	s_and_b64 s[50:51], exec, s[78:79]
	s_brev_b32 s6, 16
	s_cselect_b32 s23, s6, 0xc002800
	s_add_u32 s6, s92, s23
	s_addc_u32 s17, s93, 0
	s_and_b64 s[50:51], exec, s[78:79]
	s_cselect_b32 vcc_lo, 0x800, s59
	s_lshl_b32 s18, s30, 9
	s_add_u32 s19, s6, s18
	s_addc_u32 s28, s17, 0
	s_lshl_b32 s6, s8, 3
	s_and_b32 s50, s6, 0xfffffc00
	s_ashr_i32 s51, s50, 31
	s_lshl_b64 s[50:51], s[50:51], 1
	s_add_u32 s6, s24, s50
	s_addc_u32 s17, s25, s51
	s_add_u32 s6, s6, s18
	s_addc_u32 s17, s17, 0
	s_lshl_b32 s18, vcc_hi, 6
	s_add_u32 s82, s6, s18
	s_addc_u32 s83, s17, 0
	s_lshl_b32 s35, s22, 12
	s_waitcnt vmcnt(5)
	v_cvt_pk_bf16_f32 v2, v12, v13
	v_cvt_pk_bf16_f32 v3, v14, v15
	s_waitcnt vmcnt(2)
	v_cvt_pk_bf16_f32 v36, v20, v21
	v_cvt_pk_bf16_f32 v37, v22, v23
	s_and_b32 s17, s35, 0x3000
	v_cvt_pk_bf16_f32 v32, v8, v9
	v_cvt_pk_bf16_f32 v33, v10, v11
	ds_write2_b64 v228, v[2:3], v[36:37] offset1:4
	s_waitcnt vmcnt(1)
	v_cvt_pk_bf16_f32 v2, v28, v29
	v_cvt_pk_bf16_f32 v3, v30, v31
	v_add_u32_e32 v0, 0x2000, v228
	v_cvt_pk_bf16_f32 v34, v16, v17
	v_cvt_pk_bf16_f32 v35, v18, v19
	ds_write2_b64 v0, v[32:33], v[2:3] offset0:64 offset1:68
	s_waitcnt vmcnt(0)
	v_cvt_pk_bf16_f32 v2, v24, v25
	v_cvt_pk_bf16_f32 v3, v26, v27
	v_add_u32_e32 v0, 0x4000, v228
	s_mul_i32 s6, s17, vcc_lo
	ds_write2_b64 v0, v[34:35], v[2:3] offset0:128 offset1:132
	v_mul_lo_u32 v0, vcc_lo, v145
	s_lshl_b32 s50, vcc_lo, 5
	s_lshl_b32 s6, s6, 1
	v_or_b32_e32 v0, v0, v147
	s_add_u32 s52, s19, s6
	v_lshlrev_b32_e32 v0, 1, v0
	s_addc_u32 s53, s28, 0
	s_mov_b32 s51, s27
	v_lshl_add_u64 v[2:3], s[52:53], 0, v[0:1]
	v_lshl_add_u64 v[2:3], v[2:3], 0, s[50:51]
	global_load_dwordx4 v[48:51], v0, s[52:53]
	global_load_dwordx4 v[52:55], v[2:3], off
	v_lshl_add_u64 v[2:3], v[2:3], 0, s[50:51]
	global_load_dwordx4 v[56:59], v[2:3], off
	v_lshl_add_u64 v[2:3], v[2:3], 0, s[50:51]
	global_load_dwordx4 v[60:63], v[2:3], off
	v_mov_b32_e32 v235, 0
	s_mul_i32 s31, s17, 0x4800
	v_mov_b32_e32 v236, 0
	v_mov_b32_e32 v234, 0
	v_mov_b32_e32 v239, 0
	s_and_saveexec_b64 s[52:53], s[42:43]
	s_cbranch_execz .LBB0_590
	s_add_u32 s84, s82, s31
	s_addc_u32 s85, s83, 0
	v_lshl_add_u64 v[2:3], s[84:85], 0, v[142:143]
	global_load_dwordx2 v[154:155], v[2:3], off
	global_load_dwordx2 v[156:157], v[2:3], off offset:32
	s_cmp_eq_u32 vcc_hi, 0
	s_cselect_b64 s[84:85], -1, 0
	s_and_b64 s[84:85], s[78:79], s[84:85]
	s_and_b64 s[28:29], s[84:85], s[44:45]
	v_mov_b32_e32 v239, 0
	v_mov_b32_e32 v234, 0
	v_mov_b32_e32 v236, 0
	v_mov_b32_e32 v235, 0
	s_and_saveexec_b64 s[84:85], s[28:29]
	s_cbranch_execz .LBB0_589
	v_or_b32_e32 v2, s35, v159
	v_readlane_b32 s18, v251, 29
	v_lshlrev_b32_e32 v2, 2, v2
	v_mov_b32_e32 v3, v1
	v_readlane_b32 s19, v251, 30
	s_lshl_b32 s28, s30, 2
	s_mov_b32 s29, s27
	v_lshl_add_u64 v[32:33], v[2:3], 2, s[18:19]
	v_lshl_add_u64 v[32:33], v[32:33], 0, s[28:29]
	v_lshl_add_u64 v[2:3], v[2:3], 4, s[20:21]
	s_lshl_b32 s28, s30, 4
	s_lshl_b64 s[18:19], s[26:27], 4
	s_mov_b64 s[58:59], s[20:21]
	v_readlane_b32 s20, v251, 17
	v_readlane_b32 s21, v251, 18
	s_add_u32 s18, s20, s18
	v_lshl_add_u64 v[2:3], v[2:3], 0, s[28:29]
	s_addc_u32 s19, s21, s19
	v_mov_b32_e32 v34, s28
	global_load_dword v239, v[32:33], off
	global_load_dword v234, v[2:3], off
	global_load_dword v236, v[2:3], off offset:8
	global_load_dword v235, v34, s[18:19] offset:12
	s_mov_b64 s[20:21], s[58:59]
	s_movk_i32 s59, 0x2400
	s_mov_b32 s58, 0x42fc0000

; #define LAS __attribute__((address_space(3)))
; DI void phase_mixer(const Params& p, int seg, LAS unsigned char* lds, int G, int bid) {
;     ...
;             bf16x8 qf[4], cf[3][4];
; #pragma unroll
;             for (int k4 = 0; k4 < 4; ++k4) qf[k4] = *(const LAS bf16x8*)(lds + L_QI + lq * QP + 64 * (4 * ks + k4) + 16 * g4);
; #pragma unroll
;             for (int v = 0; v < 3; ++v)
; #pragma unroll
;                 for (int k4 = 0; k4 < 4; ++k4) cf[v][k4] = *(const LAS bf16x8*)(lds + L_CI + (16 * v + i16) * QP + 64 * (4 * ks + k4) + 16 * g4);
;             __builtin_amdgcn_sched_barrier(0);
.LBB0_598:
	s_or_b64 exec, exec, s[50:51]
	v_add_u32_e32 v242, s89, v163
	v_add_u32_e32 v240, s89, v224
	v_add_u32_e32 v243, s97, v163
	v_add_u32_e32 v241, s97, v224
	s_andn2_b64 vcc, exec, s[70:71]
	s_cbranch_vccnz .Lmxa_r
	ds_read_b128 v[124:127], v244 offset:17408
	ds_read_b128 v[116:119], v245
.Lmxa_r:
	ds_read_b128 v[76:79], v242
	ds_read_b128 v[96:99], v240
	ds_read_b128 v[120:123], v240 offset:8704
	ds_read_b128 v[68:71], v242 offset:64
	ds_read_b128 v[80:83], v240 offset:64
	ds_read_b128 v[104:107], v240 offset:8768
	ds_read_b128 v[72:75], v242 offset:128
	ds_read_b128 v[84:87], v240 offset:128
	ds_read_b128 v[92:95], v240 offset:8832
	ds_read_b128 v[64:67], v243
	ds_read_b128 v[100:103], v241
	ds_read_b128 v[108:111], v241 offset:8704
	v_cndmask_b32_e64 v128, 0, 1, s[0:1]
	v_mov_b32_e32 v0, 0
	v_cmp_ne_u32_e64 s[50:51], 1, v128
	s_andn2_b64 vcc, exec, s[0:1]
	v_mov_b32_e32 v128, 0
	v_mov_b32_e32 v129, 0
	v_mov_b32_e32 v130, 0
	v_mov_b32_e32 v131, 0
	v_mov_b32_e32 v132, 0
	v_mov_b32_e32 v133, 0
	v_mov_b32_e32 v134, 0
	v_mov_b32_e32 v135, 0
	s_cbranch_vccnz .LBB0_600
	v_lshlrev_b32_e32 v132, 16, v200
	v_and_b32_e32 v133, 0xffff0000, v200
	v_lshlrev_b32_e32 v134, 16, v201
	v_and_b32_e32 v135, 0xffff0000, v201
	v_lshlrev_b32_e32 v128, 16, v2
	v_and_b32_e32 v129, 0xffff0000, v2
	v_lshlrev_b32_e32 v130, 16, v3
	v_and_b32_e32 v131, 0xffff0000, v3

.LBB0_602:
	s_and_b64 vcc, exec, s[42:43]
	s_cbranch_vccnz .Lmx_wa1
	s_waitcnt vmcnt(7)
	ds_write_b128 v229, v[36:39] offset:34816
	s_waitcnt vmcnt(6)
	ds_write_b128 v230, v[32:35] offset:34816
	s_waitcnt vmcnt(5)
	ds_write_b128 v231, v[44:47] offset:34816
	s_waitcnt vmcnt(4)
	ds_write_b128 v232, v[40:43] offset:34816
	s_branch .Lmx_wa2
.Lmx_wa1:
	s_waitcnt vmcnt(10)
	ds_write_b128 v229, v[36:39] offset:34816
	s_waitcnt vmcnt(9)
	ds_write_b128 v230, v[32:35] offset:34816
	s_waitcnt vmcnt(8)
	ds_write_b128 v231, v[44:47] offset:34816
	s_waitcnt vmcnt(7)
	ds_write_b128 v232, v[40:43] offset:34816
	s_waitcnt vmcnt(6)

; DI void phase_mixer(const Params& p, int seg, LAS unsigned char* lds, int G, int bid) {
;     ...
;                 s16x4 t0[4], t1r[4], tv[12];
;                 int lnB = lane;
;                 const int j16 = lnB & 15, h4 = lnB >> 4;
;                 const unsigned addr0 = ldsb + L_KI + (8 * h4 + (j16 >> 2)) * QP + (2 * wave) * 32 + 8 * (lnB & 3);
;                 const unsigned addrv = ldsb + L_VI + (8 * h4 + (j16 >> 2)) * VP2 + 8 * (lnB & 3);
;                 asm volatile("ds_read_b64_tr_b16 %0, %8\n\tds_read_b64_tr_b16 %1, %8 offset:2112\n\tds_read_b64_tr_b16 %2, %8 offset:16896\n\tds_read_b64_tr_b16 %3, %8 offset:19008\n\t"
;                              "ds_read_b64_tr_b16 %4, %8 offset:32\n\tds_read_b64_tr_b16 %5, %8 offset:2144\n\tds_read_b64_tr_b16 %6, %8 offset:16928\n\tds_read_b64_tr_b16 %7, %8 offset:19040\n\ts_waitcnt lgkmcnt(0)"
;                              : "=&v"(t0[0]), "=&v"(t0[1]), "=&v"(t0[2]), "=&v"(t0[3]), "=&v"(t1r[0]), "=&v"(t1r[1]), "=&v"(t1r[2]), "=&v"(t1r[3]) : "v"(addr0) : "memory");
.LBB0_610:
	ds_read_b64_tr_b16 v[76:77], v221
	ds_read_b64_tr_b16 v[78:79], v221 offset:2176
	ds_read_b64_tr_b16 v[68:69], v221 offset:17408
	ds_read_b64_tr_b16 v[70:71], v221 offset:19584
	ds_read_b64_tr_b16 v[72:73], v221 offset:32
	ds_read_b64_tr_b16 v[74:75], v221 offset:2208
	ds_read_b64_tr_b16 v[64:65], v221 offset:17440
	ds_read_b64_tr_b16 v[66:67], v221 offset:19616
	s_waitcnt lgkmcnt(0)
	ds_read_b64_tr_b16 v[100:101], v222
	ds_read_b64_tr_b16 v[102:103], v222 offset:448
	ds_read_b64_tr_b16 v[88:89], v222 offset:3584
	ds_read_b64_tr_b16 v[90:91], v222 offset:4032
	ds_read_b64_tr_b16 v[96:97], v222 offset:32
	ds_read_b64_tr_b16 v[98:99], v222 offset:480
	ds_read_b64_tr_b16 v[84:85], v222 offset:3616
	ds_read_b64_tr_b16 v[86:87], v222 offset:4064
	s_waitcnt lgkmcnt(0)
	s_nop 0
	v_mfma_f32_16x16x32_bf16 v[12:15], v[76:79], v[100:103], v[12:15]
	s_and_b64 vcc, exec, s[42:43]
	s_cbranch_vccnz .Lmx_wm1
	s_waitcnt vmcnt(6)
	s_branch .Lmx_wm2

; DI void phase_mixer(const Params& p, int seg, LAS unsigned char* lds, int G, int bid) {
;     ...
;                 for (int v = 0; v < 3; ++v) if (v < nvt) {
;                     const bf16x8 vb0 = __builtin_shufflevector(tv[4 * v], tv[4 * v + 1], 0, 1, 2, 3, 4, 5, 6, 7);
;                     C[0][v] = __builtin_amdgcn_mfma_f32_16x16x32_bf16(__builtin_shufflevector(t0[0], t0[1], 0, 1, 2, 3, 4, 5, 6, 7), vb0, C[0][v], 0, 0, 0);
;                     C[1][v] = __builtin_amdgcn_mfma_f32_16x16x32_bf16(__builtin_shufflevector(t1r[0], t1r[1], 0, 1, 2, 3, 4, 5, 6, 7), vb0, C[1][v], 0, 0, 0); }
; #pragma unroll
;                 for (int v = 0; v < 3; ++v) if (v < nvt) {
;                     const bf16x8 vb1 = __builtin_shufflevector(tv[4 * v + 2], tv[4 * v + 3], 0, 1, 2, 3, 4, 5, 6, 7);
;                     C[0][v] = __builtin_amdgcn_mfma_f32_16x16x32_bf16(__builtin_shufflevector(t0[2], t0[3], 0, 1, 2, 3, 4, 5, 6, 7), vb1, C[0][v], 0, 0, 0);
;                     C[1][v] = __builtin_amdgcn_mfma_f32_16x16x32_bf16(__builtin_shufflevector(t1r[2], t1r[3], 0, 1, 2, 3, 4, 5, 6, 7), vb1, C[1][v], 0, 0, 0); }
;             }
; #pragma unroll
;             for (int a = 0; a < 2; ++a)
; #pragma unroll
;                 for (int v = 0; v < 3; ++v) C[a][v] = C[a][v] * g_c;
;             MX_WRITE_CIMG(1.0f);
.Lmx_wm2:
	v_max_f32_e32 v0, v234, v234
	s_add_u32 s35, s35, 64
	s_addc_u32 s22, s22, 0
	v_mfma_f32_16x16x32_bf16 v[8:11], v[76:79], v[96:99], v[8:11]
	s_add_i32 s23, s23, -1
	s_mov_b64 s[18:19], 0x1000
	v_lshl_add_u64 v[172:173], v[172:173], 0, s[54:55]
	v_lshl_add_u64 v[174:175], v[174:175], 0, s[56:57]
	v_lshl_add_u64 v[176:177], v[176:177], 0, s[18:19]
	v_lshl_add_u64 v[178:179], v[178:179], 0, s[54:55]
	v_mfma_f32_16x16x32_bf16 v[20:23], v[72:75], v[100:103], v[20:23]
	v_lshl_add_u64 v[182:183], v[182:183], 0, s[56:57]
	v_lshl_add_u64 v[180:181], v[180:181], 0, s[56:57]
	v_lshl_add_u64 v[184:185], v[184:185], 0, s[26:27]
	v_mfma_f32_16x16x32_bf16 v[28:31], v[72:75], v[96:99], v[28:31]
	v_lshl_add_u64 v[186:187], v[186:187], 0, s[26:27]
	v_lshl_add_u64 v[188:189], v[188:189], 0, s[26:27]
	v_lshl_add_u64 v[190:191], v[190:191], 0, s[26:27]
	v_mfma_f32_16x16x32_bf16 v[12:15], v[68:71], v[88:91], v[12:15]
	v_lshl_add_u64 v[192:193], v[192:193], 0, s[26:27]
	v_lshl_add_u64 v[194:195], v[194:195], 0, s[26:27]
	v_lshl_add_u64 v[196:197], v[196:197], 0, s[26:27]
	s_nop 4
	v_pk_mul_f32 v[14:15], v[158:159], v[14:15] op_sel_hi:[0,1]
	v_pk_mul_f32 v[12:13], v[158:159], v[12:13] op_sel_hi:[0,1]
	v_mfma_f32_16x16x32_bf16 v[8:11], v[68:71], v[84:87], v[8:11]
	v_cvt_pk_bf16_f32 v2, v12, v13
	v_cvt_pk_bf16_f32 v3, v14, v15
	ds_write_b64 v228, v[2:3]
	v_lshl_add_u64 v[198:199], v[198:199], 0, s[26:27]
	s_nop 3
	v_pk_mul_f32 v[10:11], v[158:159], v[10:11] op_sel_hi:[0,1]
	v_pk_mul_f32 v[8:9], v[158:159], v[8:9] op_sel_hi:[0,1]
	v_mfma_f32_16x16x32_bf16 v[20:23], v[64:67], v[88:91], v[20:23]
	v_cvt_pk_bf16_f32 v2, v8, v9
	v_mfma_f32_16x16x32_bf16 v[28:31], v[64:67], v[84:87], v[28:31]
	v_cvt_pk_bf16_f32 v3, v10, v11
	s_nop 4
	v_pk_mul_f32 v[22:23], v[158:159], v[22:23] op_sel_hi:[0,1]
	v_pk_mul_f32 v[20:21], v[158:159], v[20:21] op_sel_hi:[0,1]
	ds_write_b64 v228, v[2:3] offset:8704
	v_pk_mul_f32 v[30:31], v[158:159], v[30:31] op_sel_hi:[0,1]
	v_pk_mul_f32 v[28:29], v[158:159], v[28:29] op_sel_hi:[0,1]
	v_cvt_pk_bf16_f32 v2, v20, v21
	v_cvt_pk_bf16_f32 v3, v22, v23
	ds_write_b64 v233, v[2:3]
	v_cvt_pk_bf16_f32 v2, v28, v29
	v_cvt_pk_bf16_f32 v3, v30, v31
	ds_write_b64 v233, v[2:3] offset:8704
	s_cmp_lg_u32 s32, 0
	s_cbranch_scc0 .Lmxb_noown
	ds_read_b64_tr_b16 v[92:93], v222 offset:64
	ds_read_b64_tr_b16 v[94:95], v222 offset:512
	ds_read_b64_tr_b16 v[80:81], v222 offset:3648
	ds_read_b64_tr_b16 v[82:83], v222 offset:4096
	s_waitcnt lgkmcnt(0)
	v_mfma_f32_16x16x32_bf16 v[16:19], v[76:79], v[92:95], v[16:19]
	v_mfma_f32_16x16x32_bf16 v[24:27], v[72:75], v[92:95], v[24:27]
	v_mfma_f32_16x16x32_bf16 v[16:19], v[68:71], v[80:83], v[16:19]
	v_mfma_f32_16x16x32_bf16 v[24:27], v[64:67], v[80:83], v[24:27]
	s_nop 7
	s_nop 3
	v_pk_mul_f32 v[18:19], v[158:159], v[18:19] op_sel_hi:[0,1]
	v_pk_mul_f32 v[16:17], v[158:159], v[16:17] op_sel_hi:[0,1]
	v_pk_mul_f32 v[26:27], v[158:159], v[26:27] op_sel_hi:[0,1]
	v_pk_mul_f32 v[24:25], v[158:159], v[24:25] op_sel_hi:[0,1]
	v_cvt_pk_bf16_f32 v2, v16, v17
	v_cvt_pk_bf16_f32 v3, v18, v19
	ds_write_b64 v228, v[2:3] offset:17408
	v_cvt_pk_bf16_f32 v2, v24, v25
	v_cvt_pk_bf16_f32 v3, v26, v27
	ds_write_b64 v233, v[2:3] offset:17408
